# wout_v89 + static s_setprio 1 for the younger workgroup of each CU pair (blockIdx>=256) during the phase-1 main tile loop
# baseline (speedup 1.0000x reference)
.LBB0_95:
	s_or_b64 exec, exec, s[0:1]
	s_and_b32 s28, s2, 7
	s_xor_b32 s0, s28, 7
	s_add_i32 s0, s22, s0
	s_ashr_i32 s1, s0, 31
	s_lshr_b32 s1, s1, 29
	s_add_i32 s0, s0, s1
	s_lshr_b32 s88, s2, 3
	s_ashr_i32 s89, s0, 3
	s_cmp_lt_i32 s22, 8
	s_cselect_b64 s[0:1], -1, 0
	v_writelane_b32 v244, s0, 2
	s_barrier
	s_nop 0
	v_writelane_b32 v244, s1, 3
	s_and_b64 s[0:1], s[0:1], exec
	s_cselect_b32 s78, s2, s28
	s_cselect_b32 s29, 0, s88
	s_cmp_gt_i32 s78, 63
	s_cselect_b64 s[0:1], -1, 0
	s_cmp_gt_u32 s29, 63
	s_cselect_b64 s[4:5], -1, 0
	s_or_b64 s[0:1], s[0:1], s[4:5]
	s_and_b64 vcc, exec, s[0:1]
	s_cbranch_vccnz .LBB0_251
	v_readlane_b32 s0, v244, 2
	s_min_i32 s79, s22, 8
	v_readlane_b32 s1, v244, 3
	s_and_b64 s[0:1], s[0:1], exec
	s_cselect_b32 s80, 1, s89
	s_add_u32 s4, s20, 0x10200000
	s_addc_u32 s5, s21, 0
	s_mov_b64 s[0:1], 0
	v_mov_b32_e32 v129, 0
	s_mov_b64 s[6:7], 0x1000
	s_mov_b64 s[8:9], 0x2000
	s_mov_b64 s[10:11], 0x3000
	s_mov_b64 s[12:13], 0x204000
	s_mov_b64 s[14:15], 0x1000
	s_mov_b64 s[16:17], 0x42000
	s_mov_b64 s[34:35], 0x10242000
	s_mov_b64 s[46:47], 0x10243000
	s_movk_i32 s81, 0x80
	s_movk_i32 s82, 0x7fff
	s_movk_i32 s83, 0x1800
	s_mov_b64 s[62:63], 0x8292000
	s_movk_i32 s84, 0x1fff
	s_movk_i32 s85, 0x1ffc
	s_mov_b64 s[64:65], 0x8100000
	s_movk_i32 s86, 0x110
	v_mov_b32_e32 v140, 0x70
	s_mov_b32 s87, s29
	s_cmp_lt_u32 s2, 0x100
	s_cbranch_scc1 .Lp1prio_skip
	s_setprio 1
.Lp1prio_skip:
	s_branch .LBB0_98

.LBB0_251:
	s_setprio 0
	s_cmpk_gt_i32 s2, 0xa0
	v_writelane_b32 v244, s94, 4
	s_nop 1
	v_writelane_b32 v244, s95, 5
	s_cbranch_scc1 .LBB0_411
	s_add_u32 s4, s20, 0x10200000
	s_addc_u32 s5, s21, 0
	s_add_u32 s6, s20, 0x10c40000
	s_addc_u32 s7, s21, 0
	s_lshl_b32 s0, s2, 8
	s_add_i32 s29, s0, 0xffffe000
	s_lshl_b32 s84, s22, 8
	s_lshl_b32 s85, s2, 7
	s_lshl_b32 s86, s22, 7
	v_mov_b32_e32 v129, 0
	s_mov_b64 s[8:9], 0x1000
	s_mov_b64 s[98:99], 0x1000
	s_mov_b64 s[10:11], 0x200000
	s_mov_b64 s[12:13], 0x201000
	s_mov_b64 s[14:15], 0x202000
	s_mov_b64 s[16:17], 0x203000
	s_mov_b64 s[34:35], 0x404000
	s_mov_b64 s[46:47], 0x405000
	s_mov_b64 s[62:63], 0x406000
	s_mov_b64 s[64:65], 0x407000
	s_mov_b64 s[68:69], 0x10242000
	s_mov_b64 s[70:71], 0x10243000
	s_movk_i32 s87, 0x7fff
	s_movk_i32 s90, 0x1800
	s_mov_b64 s[72:73], 0x8292000
	s_movk_i32 s91, 0x1fff
	s_movk_i32 s92, 0x1ffc
	s_mov_b64 s[74:75], 0x8100000
	s_movk_i32 s93, 0x80
	s_movk_i32 s94, 0x110
	s_brev_b32 s95, 8
	v_mov_b32_e32 v140, 0x70
	s_mov_b32 s96, s2
	s_branch .LBB0_255
